# attention row-max cross-half exchange via v_permlane32_swap instead of ds_bpermute round trip
# speedup vs baseline: 1.0131x; 1.0021x over previous
; template <int DQ>
; __device__ __forceinline__ void attn_unit(LAS unsigned char* lds, const AttnDesc& A, int tid_in, int wid, int lane_in) {
;     ...
;             float mxa = fmaxf(fmaxf(s0[0], s0[1]), s0[2]), mxb = fmaxf(fmaxf(s1[0], s1[1]), s1[2]);
;             mxa = fmaxf(fmaxf(mxa, s0[3]), s0[4]); mxb = fmaxf(fmaxf(mxb, s1[3]), s1[4]);
;             mxa = fmaxf(fmaxf(mxa, s0[5]), s0[6]); mxb = fmaxf(fmaxf(mxb, s1[5]), s1[6]);
;             mxa = fmaxf(fmaxf(mxa, s0[7]), s0[8]); mxb = fmaxf(fmaxf(mxb, s1[7]), s1[8]);
;             mxa = fmaxf(fmaxf(mxa, s0[9]), s0[10]); mxb = fmaxf(fmaxf(mxb, s1[9]), s1[10]);
;             mxa = fmaxf(fmaxf(mxa, s0[11]), s0[12]); mxb = fmaxf(fmaxf(mxb, s1[11]), s1[12]);
;             mxa = fmaxf(fmaxf(mxa, s0[13]), s0[14]); mxb = fmaxf(fmaxf(mxb, s1[13]), s1[14]);
;             float mx = fmaxf(fmaxf(mxa, mxb), fmaxf(s0[15], s1[15]));
;             mx = fmaxf(mx, __shfl_xor(mx, 32));
;             if (__builtin_amdgcn_ballot_w64(mx > mrun + 8.0f) != 0ull) {
;                 const float mnew = fmaxf(mrun, mx);
;                 const float alpha = __builtin_amdgcn_exp2f(mrun - mnew);
;                 mrun = mnew; lrun *= alpha;
; #pragma unroll
;                 for (int r = 0; r < 16; ++r) { o0[r] *= alpha; o1[r] *= alpha; }
;             }
.LBB0_132:
	v_max3_f32 v0, v66, v67, v68
	v_max3_f32 v2, v82, v83, v84
	v_max3_f32 v0, v0, v69, v70
	v_max3_f32 v2, v2, v85, v86
	v_max3_f32 v0, v0, v71, v72
	v_max3_f32 v2, v2, v87, v88
	v_max3_f32 v0, v0, v73, v74
	v_max3_f32 v2, v2, v89, v90
	v_max3_f32 v0, v0, v75, v76
	v_max3_f32 v2, v2, v91, v92
	v_max3_f32 v0, v0, v77, v78
	v_max3_f32 v2, v2, v93, v94
	v_max_f32_e32 v3, v97, v97
	v_max_f32_e32 v4, v81, v81
	v_max3_f32 v0, v0, v79, v80
	v_max3_f32 v2, v2, v95, v96
	v_max_f32_e32 v3, v4, v3
	v_max3_f32 v0, v0, v2, v3
	v_mov_b32_e32 v2, v0
	s_nop 1
	v_permlane32_swap_b32_e32 v2, v0
	v_max_f32_e32 v0, v0, v2
	v_cmp_gt_f32_e32 vcc, v0, v213
	s_cbranch_vccz .LBB0_134
	v_sub_f32_e32 v0, v0, v16
	v_max_f32_e32 v0, v0, v0
	v_max_f32_e32 v2, v212, v212
	v_max_f32_e32 v2, v2, v0
	v_sub_f32_e32 v0, v212, v2
	v_exp_f32_e32 v0, v0
	v_mov_b32_e32 v212, v2
	v_add_f32_e32 v3, v2, v16
	v_cmp_lt_f32_e32 vcc, 0xefa18f08, v2
	v_mov_b32_e32 v5, 0x41000000
	v_pk_mul_f32 v[62:63], v[62:63], v[0:1] op_sel_hi:[1,0]
	v_pk_mul_f32 v[60:61], v[60:61], v[0:1] op_sel_hi:[1,0]
	v_pk_mul_f32 v[58:59], v[58:59], v[0:1] op_sel_hi:[1,0]
	v_pk_mul_f32 v[56:57], v[56:57], v[0:1] op_sel_hi:[1,0]
	v_pk_mul_f32 v[54:55], v[54:55], v[0:1] op_sel_hi:[1,0]
	v_pk_mul_f32 v[52:53], v[52:53], v[0:1] op_sel_hi:[1,0]
	v_pk_mul_f32 v[50:51], v[50:51], v[0:1] op_sel_hi:[1,0]
	v_pk_mul_f32 v[48:49], v[48:49], v[0:1] op_sel_hi:[1,0]
	v_pk_mul_f32 v[46:47], v[46:47], v[0:1] op_sel_hi:[1,0]
	v_pk_mul_f32 v[44:45], v[44:45], v[0:1] op_sel_hi:[1,0]
	v_pk_mul_f32 v[42:43], v[42:43], v[0:1] op_sel_hi:[1,0]
	v_pk_mul_f32 v[40:41], v[40:41], v[0:1] op_sel_hi:[1,0]
	v_pk_mul_f32 v[38:39], v[38:39], v[0:1] op_sel_hi:[1,0]
	v_pk_mul_f32 v[36:37], v[36:37], v[0:1] op_sel_hi:[1,0]
	v_pk_mul_f32 v[34:35], v[34:35], v[0:1] op_sel_hi:[1,0]
	v_pk_mul_f32 v[32:33], v[32:33], v[0:1] op_sel_hi:[1,0]
	v_mul_f32_e32 v64, v64, v0
	v_cndmask_b32_e32 v4, 0, v2, vcc
	v_cndmask_b32_e32 v213, v241, v5, vcc
	v_sub_f32_e32 v66, v66, v3
	v_sub_f32_e32 v67, v67, v3
	v_sub_f32_e32 v68, v68, v3
	v_sub_f32_e32 v69, v69, v3
	v_sub_f32_e32 v70, v70, v3
	v_sub_f32_e32 v71, v71, v3
	v_sub_f32_e32 v72, v72, v3
	v_sub_f32_e32 v73, v73, v3
	v_sub_f32_e32 v74, v74, v3
	v_sub_f32_e32 v75, v75, v3
	v_sub_f32_e32 v76, v76, v3
	v_sub_f32_e32 v77, v77, v3
	v_sub_f32_e32 v78, v78, v3
	v_sub_f32_e32 v79, v79, v3
	v_sub_f32_e32 v80, v80, v3
	v_sub_f32_e32 v81, v81, v3
	v_sub_f32_e32 v82, v82, v3
	v_sub_f32_e32 v83, v83, v3
	v_sub_f32_e32 v84, v84, v3
	v_sub_f32_e32 v85, v85, v3
	v_sub_f32_e32 v86, v86, v3
	v_sub_f32_e32 v87, v87, v3
	v_sub_f32_e32 v88, v88, v3
	v_sub_f32_e32 v89, v89, v3
	v_sub_f32_e32 v90, v90, v3
	v_sub_f32_e32 v91, v91, v3
	v_sub_f32_e32 v92, v92, v3
	v_sub_f32_e32 v93, v93, v3
	v_sub_f32_e32 v94, v94, v3
	v_sub_f32_e32 v95, v95, v3
	v_sub_f32_e32 v96, v96, v3
	v_sub_f32_e32 v97, v97, v3
	v_sub_f32_e32 v16, 0, v4
	v_sub_f32_e32 v17, 0, v4
	v_sub_f32_e32 v18, 0, v4
	v_sub_f32_e32 v19, 0, v4
	v_sub_f32_e32 v20, 0, v4
	v_sub_f32_e32 v21, 0, v4
	v_sub_f32_e32 v22, 0, v4
	v_sub_f32_e32 v23, 0, v4
	v_sub_f32_e32 v24, 0, v4
	v_sub_f32_e32 v25, 0, v4
	v_sub_f32_e32 v26, 0, v4
	v_sub_f32_e32 v27, 0, v4
	v_sub_f32_e32 v28, 0, v4
	v_sub_f32_e32 v29, 0, v4
	v_sub_f32_e32 v30, 0, v4
	v_sub_f32_e32 v31, 0, v4

; #define MLA_PACK(S, q) __builtin_bit_cast(bf16x8, (u32x4){cvt_pk_bf16_m(S[8 * (q) + 0], S[8 * (q) + 1]), cvt_pk_bf16_m(S[8 * (q) + 2], S[8 * (q) + 3]), cvt_pk_bf16_m(S[8 * (q) + 4], S[8 * (q) + 5]), cvt_pk_bf16_m(S[8 * (q) + 6], S[8 * (q) + 7])})
; #define MLA_MM(PF, VA, VC) do { o0 = __builtin_amdgcn_mfma_f32_32x32x16_bf16(VA, PF, o0, 0, 0, 0); o1 = __builtin_amdgcn_mfma_f32_32x32x16_bf16(VC, PF, o1, 0, 0, 0); } while (0)
; __device__ __forceinline__ void attn_unit_mla(LAS unsigned char* lds, const AttnDesc& A, int tid_in, int wid, int lane_in) {
;     ...
;         float ra = 0.f, rb = 0.f;
; #pragma unroll
;         for (int r = 0; r < 16; ++r) { s0[r] = __builtin_amdgcn_exp2f(s0[r] - mrun); s1[r] = __builtin_amdgcn_exp2f(s1[r] - mrun); s2[r] = __builtin_amdgcn_exp2f(s2[r] - mrun); s3[r] = __builtin_amdgcn_exp2f(s3[r] - mrun);
;             ra += s0[r] + s1[r]; rb += s2[r] + s3[r]; }
;         lrun += ra + rb;
;     ...
;         __builtin_amdgcn_s_setprio(1);
;     ...
;         { bf16x8 va1, vc1;
;           { const bf16x8 p = MLA_PACK(s0, 0); MLA_VRD(va1, vc1, vbuf, 1); MLA_MM(p, va0, vc0); }
.LBB0_152:
	v_exp_f32_e32 v188, v66
	v_exp_f32_e32 v183, v82
	v_exp_f32_e32 v189, v50
	v_exp_f32_e32 v182, v34
	v_exp_f32_e32 v190, v83
	v_exp_f32_e32 v192, v51
	v_exp_f32_e32 v191, v67
	v_exp_f32_e32 v194, v84
	v_exp_f32_e32 v193, v35
	v_exp_f32_e32 v195, v68
	v_exp_f32_e32 v196, v52
	v_exp_f32_e32 v197, v36
	v_add_f32_e32 v34, v188, v183
	v_add_f32_e32 v50, v182, v189
	v_add_f32_e32 v34, 0, v34
	v_add_f32_e32 v35, 0, v50
	v_add_f32_e32 v50, v191, v190
	v_add_f32_e32 v34, v50, v34
	v_add_f32_e32 v50, v193, v192
	v_add_f32_e32 v36, v195, v194
	v_add_f32_e32 v35, v50, v35
	v_add_f32_e32 v34, v36, v34
	v_add_f32_e32 v36, v197, v196
	v_add_f32_e32 v35, v36, v35
	v_exp_f32_e32 v198, v85
	v_exp_f32_e32 v199, v69
	v_exp_f32_e32 v200, v53
	v_exp_f32_e32 v201, v37
	v_add_f32_e32 v36, v199, v198
	v_add_f32_e32 v185, v36, v34
	v_exp_f32_e32 v202, v86
	v_exp_f32_e32 v203, v70
	v_exp_f32_e32 v204, v54
	v_exp_f32_e32 v205, v38
	v_add_f32_e32 v34, v201, v200
	v_add_f32_e32 v184, v34, v35
	v_exp_f32_e32 v83, v87
	v_exp_f32_e32 v51, v71
	v_exp_f32_e32 v82, v55
	v_exp_f32_e32 v50, v39
	v_exp_f32_e32 v85, v88
	v_exp_f32_e32 v53, v72
	v_exp_f32_e32 v84, v56
	v_exp_f32_e32 v52, v40
	v_exp_f32_e32 v87, v89
	v_exp_f32_e32 v55, v73
	v_exp_f32_e32 v86, v57
	v_exp_f32_e32 v54, v41
	v_exp_f32_e32 v67, v90
	v_exp_f32_e32 v35, v74
	v_exp_f32_e32 v69, v91
	v_exp_f32_e32 v66, v58
	v_mov_b32_e32 v34, v42
	v_exp_f32_e32 v37, v75
	v_mov_b32_e32 v36, v59
	v_exp_f32_e32 v59, v92
	v_exp_f32_e32 v71, v93
	v_exp_f32_e32 v39, v76
	v_exp_f32_e32 v41, v77
	v_mov_b32_e32 v40, v61
	v_exp_f32_e32 v61, v94
	v_exp_f32_e32 v68, v36
	v_mov_b32_e32 v36, v43
	v_exp_f32_e32 v58, v60
	v_mov_b32_e32 v38, v44
	v_exp_f32_e32 v43, v78
	v_exp_f32_e32 v60, v62
	v_mov_b32_e32 v42, v46
	v_exp_f32_e32 v73, v95
	v_exp_f32_e32 v70, v40
	v_mov_b32_e32 v40, v45
	v_exp_f32_e32 v45, v79
	v_mov_b32_e32 v44, v63
	v_exp_f32_e32 v63, v96
	v_exp_f32_e32 v72, v44
	v_mov_b32_e32 v44, v47
	v_exp_f32_e32 v47, v80
	v_exp_f32_e32 v62, v64
	v_mov_b32_e32 v46, v48
	v_exp_f32_e32 v75, v97
	v_exp_f32_e32 v57, v81
	v_add_f32_e32 v187, v203, v202
	v_add_f32_e32 v186, v205, v204
	v_exp_f32_e32 v34, v34
	v_exp_f32_e32 v74, v65
	v_exp_f32_e32 v36, v36
	v_exp_f32_e32 v56, v49
	v_pk_add_f32 v[48:49], v[186:187], v[184:185]
	v_pk_add_f32 v[64:65], v[50:51], v[82:83]
	v_exp_f32_e32 v38, v38
	v_pk_add_f32 v[48:49], v[64:65], v[48:49]
	v_pk_add_f32 v[64:65], v[52:53], v[84:85]
	v_exp_f32_e32 v40, v40
	v_pk_add_f32 v[48:49], v[64:65], v[48:49]
	v_pk_add_f32 v[64:65], v[54:55], v[86:87]
	v_exp_f32_e32 v42, v42
	v_pk_add_f32 v[48:49], v[64:65], v[48:49]
	v_pk_add_f32 v[64:65], v[34:35], v[66:67]
	v_exp_f32_e32 v44, v44
	v_pk_add_f32 v[48:49], v[64:65], v[48:49]
	v_pk_add_f32 v[64:65], v[36:37], v[68:69]
	v_exp_f32_e32 v46, v46
	v_pk_add_f32 v[48:49], v[64:65], v[48:49]
	v_pk_add_f32 v[64:65], v[38:39], v[58:59]
	s_nop 0
	v_pk_add_f32 v[48:49], v[64:65], v[48:49]
	v_pk_add_f32 v[64:65], v[40:41], v[70:71]
	s_nop 0
	v_pk_add_f32 v[48:49], v[64:65], v[48:49]
	v_pk_add_f32 v[64:65], v[42:43], v[60:61]
	s_nop 0
	v_pk_add_f32 v[48:49], v[64:65], v[48:49]
	v_pk_add_f32 v[64:65], v[44:45], v[72:73]
	s_nop 0
	v_pk_add_f32 v[48:49], v[64:65], v[48:49]
	v_pk_add_f32 v[64:65], v[46:47], v[62:63]
	s_nop 0
	v_pk_add_f32 v[48:49], v[64:65], v[48:49]
	v_pk_add_f32 v[64:65], v[56:57], v[74:75]
	s_nop 0
	v_pk_add_f32 v[48:49], v[64:65], v[48:49]
	s_nop 0
	v_add_f32_e32 v48, v48, v49
	v_add_f32_e32 v178, v178, v48
	s_setprio 1
	v_cvt_pk_bf16_f32 v76, v183, v190
	v_cvt_pk_bf16_f32 v77, v194, v198
	v_cvt_pk_bf16_f32 v78, v202, v83
	v_cvt_pk_bf16_f32 v79, v85, v87
	v_cvt_pk_bf16_f32 v88, v67, v69
	v_cvt_pk_bf16_f32 v89, v59, v71
	s_waitcnt lgkmcnt(0)
; #define MLA_PACK(S, q) __builtin_bit_cast(bf16x8, (u32x4){cvt_pk_bf16_m(S[8 * (q) + 0], S[8 * (q) + 1]), cvt_pk_bf16_m(S[8 * (q) + 2], S[8 * (q) + 3]), cvt_pk_bf16_m(S[8 * (q) + 4], S[8 * (q) + 5]), cvt_pk_bf16_m(S[8 * (q) + 6], S[8 * (q) + 7])})
; #define MLA_MM(PF, VA, VC) do { o0 = __builtin_amdgcn_mfma_f32_32x32x16_bf16(VA, PF, o0, 0, 0, 0); o1 = __builtin_amdgcn_mfma_f32_32x32x16_bf16(VC, PF, o1, 0, 0, 0); } while (0)
; __device__ __forceinline__ void attn_unit_mla(LAS unsigned char* lds, const AttnDesc& A, int tid_in, int wid, int lane_in) {
;     ...
;         { bf16x8 va1, vc1;
;           { const bf16x8 p = MLA_PACK(s0, 0); MLA_VRD(va1, vc1, vbuf, 1); MLA_MM(p, va0, vc0); }
;           { const bf16x8 p = MLA_PACK(s0, 1); MLA_VRD(va0, vc0, vbuf, 2); MLA_MM(p, va1, vc1); }
;           { const bf16x8 p = MLA_PACK(s1, 0); MLA_VRD(va1, vc1, vbuf, 3); MLA_MM(p, va0, vc0); }
;           { const bf16x8 p = MLA_PACK(s1, 1); MLA_VRD(va0, vc0, vbuf + 8192, 0); MLA_MM(p, va1, vc1); }
;           { const bf16x8 p = MLA_PACK(s2, 0); MLA_VRD(va1, vc1, vbuf + 8192, 1); MLA_MM(p, va0, vc0); }
;           { const bf16x8 p = MLA_PACK(s2, 1); MLA_VRD(va0, vc0, vbuf + 8192, 2); MLA_MM(p, va1, vc1); }
;           { const bf16x8 p = MLA_PACK(s3, 0); MLA_VRD(va1, vc1, vbuf + 8192, 3); MLA_MM(p, va0, vc0); }
;           { const bf16x8 p = MLA_PACK(s3, 1); MLA_MM(p, va1, vc1); } }
;         __builtin_amdgcn_s_setprio(0);
	v_mfma_f32_32x32x16_bf16 v[2:17], v[150:153], v[76:79], v[2:17]
	v_cvt_pk_bf16_f32 v90, v61, v73
	v_cvt_pk_bf16_f32 v91, v63, v75
	v_cvt_pk_bf16_f32 v68, v66, v68
	v_cvt_pk_bf16_f32 v69, v58, v70
	v_cvt_pk_bf16_f32 v70, v60, v72
	v_cvt_pk_bf16_f32 v71, v62, v74
	v_cvt_pk_bf16_f32 v48, v182, v193
	v_mfma_f32_32x32x16_bf16 v[18:33], v[146:149], v[76:79], v[18:33]
	ds_read_b64_tr_b16 v[76:77], v180 offset:54272
	ds_read_b64_tr_b16 v[78:79], v180 offset:54784
	v_cvt_pk_bf16_f32 v49, v197, v201
	v_cvt_pk_bf16_f32 v50, v205, v50
	v_cvt_pk_bf16_f32 v34, v34, v36
	v_cvt_pk_bf16_f32 v36, v42, v44
	s_waitcnt lgkmcnt(0)
	v_mfma_f32_32x32x16_bf16 v[2:17], v[76:79], v[88:91], v[2:17]
	ds_read_b64_tr_b16 v[76:77], v180 offset:58368
	ds_read_b64_tr_b16 v[78:79], v180 offset:58880
	ds_read_b64_tr_b16 v[92:93], v180 offset:55296
	ds_read_b64_tr_b16 v[94:95], v180 offset:55808
	s_waitcnt lgkmcnt(0)
	v_mfma_f32_32x32x16_bf16 v[18:33], v[76:79], v[88:91], v[18:33]
	v_cvt_pk_bf16_f32 v76, v188, v191
	v_cvt_pk_bf16_f32 v77, v195, v199
	v_cvt_pk_bf16_f32 v78, v203, v51
	v_cvt_pk_bf16_f32 v79, v53, v55
	ds_read_b64_tr_b16 v[88:89], v180 offset:59392
	ds_read_b64_tr_b16 v[90:91], v180 offset:59904
	ds_read_b64_tr_b16 v[80:81], v180 offset:56832
	v_cvt_pk_bf16_f32 v51, v52, v54
	v_mfma_f32_32x32x16_bf16 v[2:17], v[92:95], v[76:79], v[2:17]
	s_waitcnt lgkmcnt(0)
	v_mfma_f32_32x32x16_bf16 v[18:33], v[88:91], v[76:79], v[18:33]
	ds_read_b64_tr_b16 v[78:79], v180 offset:56320
	ds_read_b64_tr_b16 v[76:77], v180 offset:60416
	v_cvt_pk_bf16_f32 v88, v35, v37
	v_cvt_pk_bf16_f32 v89, v39, v41
	v_cvt_pk_bf16_f32 v90, v43, v45
	v_cvt_pk_bf16_f32 v91, v47, v57
	v_add_u32_e32 v39, 0xf000, v180
	v_cvt_pk_bf16_f32 v35, v38, v40
	s_waitcnt lgkmcnt(0)
	v_mfma_f32_32x32x16_bf16 v[2:17], v[78:81], v[88:91], v[2:17]
	ds_read_b64_tr_b16 v[78:79], v180 offset:60928
	ds_read_b64_tr_b16 v[92:93], v180 offset:61440
	ds_read_b64_tr_b16 v[94:95], v180 offset:61952
	v_cvt_pk_bf16_f32 v37, v46, v56
	s_waitcnt lgkmcnt(0)
	v_mfma_f32_32x32x16_bf16 v[18:33], v[76:79], v[88:91], v[18:33]
	v_cvt_pk_bf16_f32 v76, v189, v192
	v_cvt_pk_bf16_f32 v77, v196, v200
	v_cvt_pk_bf16_f32 v78, v204, v82
	v_cvt_pk_bf16_f32 v79, v84, v86
	ds_read_b64_tr_b16 v[80:81], v39 offset:4096
	ds_read_b64_tr_b16 v[82:83], v39 offset:4608
	ds_read_b64_tr_b16 v[84:85], v180 offset:62464
	ds_read_b64_tr_b16 v[86:87], v180 offset:62976
	ds_read_b64_tr_b16 v[64:65], v39 offset:5120
	ds_read_b64_tr_b16 v[66:67], v39 offset:5632
	v_mfma_f32_32x32x16_bf16 v[2:17], v[92:95], v[76:79], v[2:17]
	ds_read_b64_tr_b16 v[58:59], v180 offset:63488
	ds_read_b64_tr_b16 v[60:61], v180 offset:64000
	s_waitcnt lgkmcnt(0)
	v_mfma_f32_32x32x16_bf16 v[18:33], v[80:83], v[76:79], v[18:33]
	v_mfma_f32_32x32x16_bf16 v[2:17], v[84:87], v[68:71], v[2:17]
	v_mfma_f32_32x32x16_bf16 v[18:33], v[64:67], v[68:71], v[18:33]
	v_mfma_f32_32x32x16_bf16 v[2:17], v[58:61], v[48:51], v[2:17]
	ds_read_b64_tr_b16 v[52:53], v39 offset:6144
	ds_read_b64_tr_b16 v[54:55], v39 offset:6656
	ds_read_b64_tr_b16 v[58:59], v180 offset:64512
	s_waitcnt lgkmcnt(0)
	v_mfma_f32_32x32x16_bf16 v[18:33], v[52:55], v[48:51], v[18:33]
	ds_read_b64_tr_b16 v[60:61], v180 offset:65024
	ds_read_b64_tr_b16 v[48:49], v39 offset:7168
	ds_read_b64_tr_b16 v[50:51], v39 offset:7680
	s_waitcnt lgkmcnt(0)
	v_mfma_f32_32x32x16_bf16 v[2:17], v[58:61], v[34:37], v[2:17]
	v_mfma_f32_32x32x16_bf16 v[18:33], v[48:51], v[34:37], v[18:33]
	s_setprio 0
	s_addk_i32 s48, 0x80
	s_add_i32 s50, s50, 2
	s_add_i32 s8, s8, 1
	s_cmp_lg_u32 s49, s48
	s_cbranch_scc0 .LBB0_27

; #define MLA_KRD(SET, st_) do { const int co_ = (16 * (st_) + 8 * h) * 2; \
;             kf[SET][0] = *(const LAS bf16x8*)(kbuf + r32 * KSTR + co_); kf[SET][1] = *(const LAS bf16x8*)(kbuf + (32 + r32) * KSTR + co_); \
;             kf[SET][2] = *(const LAS bf16x8*)(kbuf + ATT_KBUF + r32 * KSTR + co_); kf[SET][3] = *(const LAS bf16x8*)(kbuf + ATT_KBUF + (32 + r32) * KSTR + co_); } while (0)
; __device__ __forceinline__ void attn_unit_mla(LAS unsigned char* lds, const AttnDesc& A, int tid_in, int wid, int lane_in) {
;     ...
;         f32x16 s0, s1, s2, s3;
; #pragma unroll
;         for (int r = 0; r < 16; ++r) { s0[r] = 0.f; s1[r] = 0.f; s2[r] = 0.f; s3[r] = 0.f; }
;         __builtin_amdgcn_s_setprio(1);
;         bf16x8 kf[2][4];
;     ...
;         MLA_KRD(0, 0);
;         __builtin_amdgcn_sched_group_barrier(0x100, 4, 0);
; #pragma unroll
;         for (int s = 0; s < NS; ++s) {
;             if (s + 1 < NS) { MLA_KRD((s + 1) & 1, s + 1); __builtin_amdgcn_sched_group_barrier(0x100, 4, 0); }
;             s0 = __builtin_amdgcn_mfma_f32_32x32x16_bf16(kf[s & 1][0], qf[s], s0, 0, 0, 0);
;             s1 = __builtin_amdgcn_mfma_f32_32x32x16_bf16(kf[s & 1][1], qf[s], s1, 0, 0, 0);
;             s2 = __builtin_amdgcn_mfma_f32_32x32x16_bf16(kf[s & 1][2], qf[s], s2, 0, 0, 0);
;             s3 = __builtin_amdgcn_mfma_f32_32x32x16_bf16(kf[s & 1][3], qf[s], s3, 0, 0, 0);
;             __builtin_amdgcn_sched_group_barrier(0x008, 4, 0);
;         }
;     ...
;         __builtin_amdgcn_s_setprio(0);
;         bf16x8 va0, vc0;
;         MLA_VRD0(va0, vc0, vbuf);
;         float m0 = fmaxf(fmaxf(s0[0], s1[0]), fmaxf(s2[0], s3[0]));
; #pragma unroll
;         for (int r = 1; r < 16; ++r) { m0 = fmaxf(fmaxf(m0, s0[r]), s1[r]); m0 = fmaxf(fmaxf(m0, s2[r]), s3[r]); }
;         float mx = fmaxf(m0, __shfl_xor(m0, 32));
;         if (__builtin_amdgcn_ballot_w64(mx > mrun + 8.0f) != 0ull) {
.LBB0_163:
	s_setprio 1
	v_add3_u32 v180, s52, v177, v0
	ds_read_b128 v[34:37], v180
	ds_read_b128 v[38:41], v180 offset:6656
	ds_read_b128 v[42:45], v180 offset:13312
	ds_read_b128 v[46:49], v180 offset:19968
	ds_read_b128 v[146:149], v180 offset:32
	ds_read_b128 v[150:153], v180 offset:6688
	ds_read_b128 v[182:185], v180 offset:13344
	ds_read_b128 v[186:189], v180 offset:20000
	s_waitcnt lgkmcnt(0)
	v_mfma_f32_32x32x16_bf16 v[82:97], v[34:37], v[98:101], v[206:221]
	v_mfma_f32_32x32x16_bf16 v[66:81], v[38:41], v[98:101], v[206:221]
	v_mfma_f32_32x32x16_bf16 v[50:65], v[42:45], v[98:101], v[206:221]
	v_mfma_f32_32x32x16_bf16 v[34:49], v[46:49], v[98:101], v[206:221]
	ds_read_b128 v[190:193], v180 offset:64
	ds_read_b128 v[194:197], v180 offset:6720
	ds_read_b128 v[198:201], v180 offset:13376
	ds_read_b128 v[202:205], v180 offset:20032
	v_mfma_f32_32x32x16_bf16 v[82:97], v[146:149], v[102:105], v[82:97]
	v_mfma_f32_32x32x16_bf16 v[66:81], v[150:153], v[102:105], v[66:81]
	v_mfma_f32_32x32x16_bf16 v[50:65], v[182:185], v[102:105], v[50:65]
	v_mfma_f32_32x32x16_bf16 v[34:49], v[186:189], v[102:105], v[34:49]
	ds_read_b128 v[146:149], v180 offset:96
	ds_read_b128 v[150:153], v180 offset:6752
	ds_read_b128 v[182:185], v180 offset:13408
	ds_read_b128 v[186:189], v180 offset:20064
	s_waitcnt lgkmcnt(0)
	v_mfma_f32_32x32x16_bf16 v[82:97], v[190:193], v[106:109], v[82:97]
	v_mfma_f32_32x32x16_bf16 v[66:81], v[194:197], v[106:109], v[66:81]
	v_mfma_f32_32x32x16_bf16 v[50:65], v[198:201], v[106:109], v[50:65]
	v_mfma_f32_32x32x16_bf16 v[34:49], v[202:205], v[106:109], v[34:49]
	ds_read_b128 v[190:193], v180 offset:128
	ds_read_b128 v[194:197], v180 offset:6784
	ds_read_b128 v[198:201], v180 offset:13440
	ds_read_b128 v[202:205], v180 offset:20096
	v_mfma_f32_32x32x16_bf16 v[82:97], v[146:149], v[110:113], v[82:97]
	v_mfma_f32_32x32x16_bf16 v[66:81], v[150:153], v[110:113], v[66:81]
	v_mfma_f32_32x32x16_bf16 v[50:65], v[182:185], v[110:113], v[50:65]
	v_mfma_f32_32x32x16_bf16 v[34:49], v[186:189], v[110:113], v[34:49]
	ds_read_b128 v[146:149], v180 offset:160
	ds_read_b128 v[150:153], v180 offset:6816
	ds_read_b128 v[182:185], v180 offset:13472
	ds_read_b128 v[186:189], v180 offset:20128
	s_waitcnt lgkmcnt(0)
	v_mfma_f32_32x32x16_bf16 v[82:97], v[190:193], v[114:117], v[82:97]
	v_mfma_f32_32x32x16_bf16 v[66:81], v[194:197], v[114:117], v[66:81]
	v_mfma_f32_32x32x16_bf16 v[50:65], v[198:201], v[114:117], v[50:65]
	v_mfma_f32_32x32x16_bf16 v[34:49], v[202:205], v[114:117], v[34:49]
	v_mfma_f32_32x32x16_bf16 v[82:97], v[146:149], v[118:121], v[82:97]
	v_mfma_f32_32x32x16_bf16 v[66:81], v[150:153], v[118:121], v[66:81]
	v_mfma_f32_32x32x16_bf16 v[50:65], v[182:185], v[118:121], v[50:65]
	v_mfma_f32_32x32x16_bf16 v[34:49], v[186:189], v[118:121], v[34:49]
	s_setprio 0
	s_nop 10
	v_max_f32_e32 v146, v34, v34
	v_max_f32_e32 v147, v50, v50
	v_max_f32_e32 v146, v147, v146
	v_max3_f32 v146, v82, v66, v146
	v_max3_f32 v146, v146, v83, v67
	v_max3_f32 v146, v146, v51, v35
	v_max3_f32 v146, v146, v84, v68
	v_max3_f32 v146, v146, v52, v36
	v_max3_f32 v146, v146, v85, v69
	v_max3_f32 v146, v146, v53, v37
	v_max3_f32 v146, v146, v86, v70
	v_max3_f32 v146, v146, v54, v38
	v_max3_f32 v146, v146, v87, v71
	v_max3_f32 v146, v146, v55, v39
	v_max3_f32 v146, v146, v88, v72
	v_max3_f32 v146, v146, v56, v40
	v_max3_f32 v146, v146, v89, v73
	v_max3_f32 v146, v146, v57, v41
	v_max3_f32 v146, v146, v90, v74
	v_max3_f32 v146, v146, v58, v42
	v_max3_f32 v146, v146, v91, v75
	v_max3_f32 v146, v146, v59, v43
	v_max3_f32 v146, v146, v92, v76
	v_max3_f32 v146, v146, v60, v44
	v_max3_f32 v146, v146, v93, v77
	v_max3_f32 v146, v146, v61, v45
	v_max3_f32 v146, v146, v94, v78
	v_max3_f32 v146, v146, v62, v46
	v_max3_f32 v146, v146, v95, v79
	v_max3_f32 v146, v146, v63, v47
	v_max3_f32 v146, v146, v96, v80
	v_max3_f32 v146, v146, v64, v48
	v_max3_f32 v146, v146, v97, v81
	v_max3_f32 v182, v146, v65, v49
	v_mov_b32_e32 v183, v182
	v_add_u32_e32 v180, s51, v161
	ds_read_b64_tr_b16 v[150:151], v180 offset:53248
	ds_read_b64_tr_b16 v[152:153], v180 offset:53760
	ds_read_b64_tr_b16 v[146:147], v180 offset:57344
	ds_read_b64_tr_b16 v[148:149], v180 offset:57856
	v_permlane32_swap_b32_e32 v183, v182
	v_max_f32_e32 v182, v182, v183
	v_cmp_gt_f32_e32 vcc, v182, v222
	s_cbranch_vccz .LBB0_152
; __device__ __forceinline__ void attn_unit_mla(LAS unsigned char* lds, const AttnDesc& A, int tid_in, int wid, int lane_in) {
;     ...
;         if (__builtin_amdgcn_ballot_w64(mx > mrun + 8.0f) != 0ull) {
;             const float mnew = fmaxf(mrun, mx);
;             const float alpha = __builtin_amdgcn_exp2f(mrun - mnew);
;             mrun = mnew; lrun *= alpha;
; #pragma unroll
;             for (int r = 0; r < 16; ++r) { o0[r] *= alpha; o1[r] *= alpha; }
;         }
	v_sub_f32_e32 v182, v182, v206
	v_max_f32_e32 v182, v182, v182
	v_max_f32_e32 v183, v179, v179
	v_max_f32_e32 v183, v183, v182
	v_sub_f32_e32 v179, v179, v183
	v_exp_f32_e32 v182, v179
	v_mov_b32_e32 v179, v183
	v_add_f32_e32 v184, v183, v206
	v_cmp_lt_f32_e32 vcc, 0xefa18f08, v183
	v_mov_b32_e32 v186, 0x41000000
	v_pk_mul_f32 v[16:17], v[16:17], v[182:183] op_sel_hi:[1,0]
	v_pk_mul_f32 v[14:15], v[14:15], v[182:183] op_sel_hi:[1,0]
	v_pk_mul_f32 v[12:13], v[12:13], v[182:183] op_sel_hi:[1,0]
	v_pk_mul_f32 v[10:11], v[10:11], v[182:183] op_sel_hi:[1,0]
	v_pk_mul_f32 v[8:9], v[8:9], v[182:183] op_sel_hi:[1,0]
	v_pk_mul_f32 v[6:7], v[6:7], v[182:183] op_sel_hi:[1,0]
	v_pk_mul_f32 v[4:5], v[4:5], v[182:183] op_sel_hi:[1,0]
	v_pk_mul_f32 v[2:3], v[2:3], v[182:183] op_sel_hi:[1,0]
	v_pk_mul_f32 v[32:33], v[32:33], v[182:183] op_sel_hi:[1,0]
	v_pk_mul_f32 v[30:31], v[30:31], v[182:183] op_sel_hi:[1,0]
	v_pk_mul_f32 v[28:29], v[28:29], v[182:183] op_sel_hi:[1,0]
	v_pk_mul_f32 v[26:27], v[26:27], v[182:183] op_sel_hi:[1,0]
	v_pk_mul_f32 v[24:25], v[24:25], v[182:183] op_sel_hi:[1,0]
	v_pk_mul_f32 v[22:23], v[22:23], v[182:183] op_sel_hi:[1,0]
	v_pk_mul_f32 v[20:21], v[20:21], v[182:183] op_sel_hi:[1,0]
	v_pk_mul_f32 v[18:19], v[18:19], v[182:183] op_sel_hi:[1,0]
	v_mul_f32_e32 v178, v178, v182
	v_cndmask_b32_e32 v185, 0, v183, vcc
	v_cndmask_b32_e32 v222, v241, v186, vcc
	v_sub_f32_e32 v34, v34, v184
	v_sub_f32_e32 v35, v35, v184
	v_sub_f32_e32 v36, v36, v184
	v_sub_f32_e32 v37, v37, v184
	v_sub_f32_e32 v38, v38, v184
	v_sub_f32_e32 v39, v39, v184
	v_sub_f32_e32 v40, v40, v184
	v_sub_f32_e32 v41, v41, v184
	v_sub_f32_e32 v42, v42, v184
	v_sub_f32_e32 v43, v43, v184
	v_sub_f32_e32 v44, v44, v184
	v_sub_f32_e32 v45, v45, v184
	v_sub_f32_e32 v46, v46, v184
	v_sub_f32_e32 v47, v47, v184
	v_sub_f32_e32 v48, v48, v184
	v_sub_f32_e32 v49, v49, v184
	v_sub_f32_e32 v50, v50, v184
	v_sub_f32_e32 v51, v51, v184
	v_sub_f32_e32 v52, v52, v184
	v_sub_f32_e32 v53, v53, v184
	v_sub_f32_e32 v54, v54, v184
	v_sub_f32_e32 v55, v55, v184
	v_sub_f32_e32 v56, v56, v184
	v_sub_f32_e32 v57, v57, v184
	v_sub_f32_e32 v58, v58, v184
	v_sub_f32_e32 v59, v59, v184
	v_sub_f32_e32 v60, v60, v184
	v_sub_f32_e32 v61, v61, v184
	v_sub_f32_e32 v62, v62, v184
	v_sub_f32_e32 v63, v63, v184
	v_sub_f32_e32 v64, v64, v184
	v_sub_f32_e32 v65, v65, v184
	v_sub_f32_e32 v66, v66, v184
	v_sub_f32_e32 v67, v67, v184
	v_sub_f32_e32 v68, v68, v184
	v_sub_f32_e32 v69, v69, v184
	v_sub_f32_e32 v70, v70, v184
	v_sub_f32_e32 v71, v71, v184
	v_sub_f32_e32 v72, v72, v184
	v_sub_f32_e32 v73, v73, v184
	v_sub_f32_e32 v74, v74, v184
	v_sub_f32_e32 v75, v75, v184
	v_sub_f32_e32 v76, v76, v184
	v_sub_f32_e32 v77, v77, v184
	v_sub_f32_e32 v78, v78, v184
	v_sub_f32_e32 v79, v79, v184
	v_sub_f32_e32 v80, v80, v184
	v_sub_f32_e32 v81, v81, v184
	v_sub_f32_e32 v82, v82, v184
	v_sub_f32_e32 v83, v83, v184
	v_sub_f32_e32 v84, v84, v184
	v_sub_f32_e32 v85, v85, v184
	v_sub_f32_e32 v86, v86, v184
	v_sub_f32_e32 v87, v87, v184
	v_sub_f32_e32 v88, v88, v184
	v_sub_f32_e32 v89, v89, v184
	v_sub_f32_e32 v90, v90, v184
	v_sub_f32_e32 v91, v91, v184
	v_sub_f32_e32 v92, v92, v184
	v_sub_f32_e32 v93, v93, v184
	v_sub_f32_e32 v94, v94, v184
	v_sub_f32_e32 v95, v95, v184
	v_sub_f32_e32 v96, v96, v184
	v_sub_f32_e32 v97, v97, v184
	v_sub_f32_e32 v206, 0, v185
	v_sub_f32_e32 v207, 0, v185
	v_sub_f32_e32 v208, 0, v185
	v_sub_f32_e32 v209, 0, v185
	v_sub_f32_e32 v210, 0, v185
	v_sub_f32_e32 v211, 0, v185
	v_sub_f32_e32 v212, 0, v185
	v_sub_f32_e32 v213, 0, v185
	v_sub_f32_e32 v214, 0, v185
	v_sub_f32_e32 v215, 0, v185
	v_sub_f32_e32 v216, 0, v185
	v_sub_f32_e32 v217, 0, v185
	v_sub_f32_e32 v218, 0, v185
	v_sub_f32_e32 v219, 0, v185
	v_sub_f32_e32 v220, 0, v185
	v_sub_f32_e32 v221, 0, v185
	s_branch .LBB0_152
